# speedup vs baseline: 1.1392x; 1.0007x over previous
; DEV void rope_cs(int pos, int i, float& c, float& s) {
;   double r = (double)pos * ROPE_REV[i];
;   r -= rint(r);
;   float rf = (float)r;
;   s = __builtin_amdgcn_sinf(rf);
;   c = __builtin_amdgcn_cosf(rf);
; }
; template <int EPI, bool AF32>
; DEV void gemm_tile(const void* Ap, int lda, const u16* Bt, int ldb, int K, int m0, int n0, const Epi& ea, char* smem) {
;     ...
;       } else if (EPI == EP_QROPE) {
;         u16* C = (u16*)ea.p0;
;         const bool isr = ((cb >> 6) % 3) == 2;
;         if (!isr) {
; #pragma unroll
;           for (int n = 0; n < 4; n++) C[(size_t)row * 1536 + cb + n * 16 + fr] = f2bf(acc[m][n][j]);
;         } else {
;           const int pos = tok_pos(row);
; #pragma unroll
;           for (int n = 0; n < 2; n++) {
;             const int i = n * 16 + fr;
;             float c, s;
;             rope_cs(pos, i, c, s);
;             const float x1 = acc[m][n][j], x2 = acc[m][n + 2][j];
;             C[(size_t)row * 1536 + cb + i] = f2bf(x1 * c - x2 * s);
;             C[(size_t)row * 1536 + cb + 32 + i] = f2bf(x1 * s + x2 * c);
;           }
;         }
.LBB0_279:
	s_or_saveexec_b64 s[0:1], s[0:1]
	v_or_b32_e32 v72, 0x1000, v72
	v_lshlrev_b32_e32 v70, 3, v70
	s_getpc_b64 s[2:3]
	s_add_u32 s2, s2, _ZL8ROPE_REV@rel32@lo+4
	s_addc_u32 s3, s3, _ZL8ROPE_REV@rel32@hi+12
	s_nop 0
	global_load_dwordx2 v[222:223], v70, s[2:3]
	global_load_dwordx2 v[224:225], v70, s[2:3] offset:128
	s_xor_b64 exec, exec, s[0:1]
	s_cbranch_execz .LBB0_281
	v_cmp_gt_i32_e64 s[2:3], s39, v71
	v_and_b32_e32 v73, 0x1fcc, v71
	s_nop 0
	v_cndmask_b32_e64 v73, v72, v73, s[2:3]
	v_mad_i64_i32 v[76:77], s[2:3], v71, s68, v[66:67]
	v_cvt_f64_u32_e32 v[74:75], v73
	s_nop 0
	v_mov_b32_e32 v78, v222
	v_mov_b32_e32 v79, v223
	v_lshl_add_u64 v[76:77], v[76:77], 0, v[0:1]
	s_waitcnt vmcnt(0)
	v_mul_f64 v[80:81], v[78:79], v[74:75]
	v_rndne_f64_e32 v[80:81], v[80:81]
	v_fma_f64 v[78:79], v[78:79], v[74:75], -v[80:81]
	v_cvt_f32_f64_e32 v73, v[78:79]
	v_sin_f32_e32 v78, v73
	v_cos_f32_e32 v73, v73
	v_mul_f32_e32 v79, v58, v78
	v_fma_f32 v79, v62, v73, -v79
	v_cvt_pk_bf16_f32 v79, v79, s0
	v_mul_f32_e32 v58, v58, v73
	global_store_short v[76:77], v79, off
	v_fmac_f32_e32 v58, v62, v78
	v_mov_b32_e32 v78, v224
	v_mov_b32_e32 v79, v225
	v_cvt_pk_bf16_f32 v58, v58, s0
	global_store_short v[76:77], v58, off offset:64
	v_mul_f64 v[80:81], v[78:79], v[74:75]
	v_rndne_f64_e32 v[80:81], v[80:81]
	v_fma_f64 v[74:75], v[78:79], v[74:75], -v[80:81]
	v_cvt_f32_f64_e32 v58, v[74:75]
	v_sin_f32_e32 v62, v58
	v_cos_f32_e32 v58, v58
	v_mul_f32_e32 v73, v54, v62
	v_mul_f32_e32 v54, v54, v58
	v_fma_f32 v73, v50, v58, -v73
	v_fmac_f32_e32 v54, v50, v62
	v_cvt_pk_bf16_f32 v73, v73, s0
	v_cvt_pk_bf16_f32 v50, v54, s0
	global_store_short v[76:77], v73, off offset:32
	global_store_short v[76:77], v50, off offset:96

; DEV void rope_cs(int pos, int i, float& c, float& s) {
;   double r = (double)pos * ROPE_REV[i];
;   r -= rint(r);
;   float rf = (float)r;
;   s = __builtin_amdgcn_sinf(rf);
;   c = __builtin_amdgcn_cosf(rf);
; }
; template <int EPI, bool AF32>
; DEV void gemm_tile(const void* Ap, int lda, const u16* Bt, int ldb, int K, int m0, int n0, const Epi& ea, char* smem) {
;     ...
;           const int pos = tok_pos(row);
; #pragma unroll
;           for (int n = 0; n < 2; n++) {
;             const int i = n * 16 + fr;
;             float c, s;
;             rope_cs(pos, i, c, s);
;             const float x1 = acc[m][n][j], x2 = acc[m][n + 2][j];
;             C[(size_t)row * 1536 + cb + i] = f2bf(x1 * c - x2 * s);
;             C[(size_t)row * 1536 + cb + 32 + i] = f2bf(x1 * s + x2 * c);
;           }
.LBB0_283:
	s_andn2_saveexec_b64 s[0:1], s[0:1]
	s_cbranch_execz .LBB0_285
	v_cmp_gt_i32_e64 s[2:3], s74, v71
	v_and_b32_e32 v54, 0x1fcd, v50
	v_and_or_b32 v58, v50, 13, v213
	v_cndmask_b32_e64 v54, v58, v54, s[2:3]
	v_mad_i64_i32 v[76:77], s[2:3], v50, s68, v[66:67]
	v_cvt_f64_u32_e32 v[74:75], v54
	s_nop 0
	v_mov_b32_e32 v78, v222
	v_mov_b32_e32 v79, v223
	v_lshl_add_u64 v[76:77], v[76:77], 0, v[0:1]
	v_mul_f64 v[80:81], v[78:79], v[74:75]
	v_rndne_f64_e32 v[80:81], v[80:81]
	v_fma_f64 v[78:79], v[78:79], v[74:75], -v[80:81]
	v_cvt_f32_f64_e32 v50, v[78:79]
	v_sin_f32_e32 v54, v50
	v_cos_f32_e32 v50, v50
	v_mul_f32_e32 v58, v59, v54
	v_fma_f32 v58, v63, v50, -v58
	v_cvt_pk_bf16_f32 v58, v58, s0
	global_store_short v[76:77], v58, off
	v_mul_f32_e32 v50, v59, v50
	v_mov_b32_e32 v58, v224
	v_mov_b32_e32 v59, v225
	v_fmac_f32_e32 v50, v63, v54
	v_cvt_pk_bf16_f32 v50, v50, s0
	global_store_short v[76:77], v50, off offset:64
	v_mul_f64 v[62:63], v[58:59], v[74:75]
	v_rndne_f64_e32 v[62:63], v[62:63]
	v_fma_f64 v[58:59], v[58:59], v[74:75], -v[62:63]
	v_cvt_f32_f64_e32 v50, v[58:59]
	v_sin_f32_e32 v54, v50
	v_cos_f32_e32 v50, v50
	v_mul_f32_e32 v58, v55, v54
	v_fma_f32 v58, v51, v50, -v58
	v_mul_f32_e32 v50, v55, v50
	v_fmac_f32_e32 v50, v51, v54
	v_cvt_pk_bf16_f32 v58, v58, s0
	v_cvt_pk_bf16_f32 v50, v50, s0
	global_store_short v[76:77], v58, off offset:32
	global_store_short v[76:77], v50, off offset:96

; DEV void rope_cs(int pos, int i, float& c, float& s) {
;   double r = (double)pos * ROPE_REV[i];
;   r -= rint(r);
;   float rf = (float)r;
;   s = __builtin_amdgcn_sinf(rf);
;   c = __builtin_amdgcn_cosf(rf);
; }
; template <int EPI, bool AF32>
; DEV void gemm_tile(const void* Ap, int lda, const u16* Bt, int ldb, int K, int m0, int n0, const Epi& ea, char* smem) {
;     ...
;           const int pos = tok_pos(row);
; #pragma unroll
;           for (int n = 0; n < 2; n++) {
;             const int i = n * 16 + fr;
;             float c, s;
;             rope_cs(pos, i, c, s);
;             const float x1 = acc[m][n][j], x2 = acc[m][n + 2][j];
;             C[(size_t)row * 1536 + cb + i] = f2bf(x1 * c - x2 * s);
;             C[(size_t)row * 1536 + cb + 32 + i] = f2bf(x1 * s + x2 * c);
;           }
.LBB0_287:
	s_andn2_saveexec_b64 s[0:1], s[0:1]
	s_cbranch_execz .LBB0_289
	s_movk_i32 s2, 0x7ffe
	v_cmp_gt_i32_e64 s[2:3], s2, v71
	v_and_b32_e32 v51, 0x1fce, v50
	v_and_or_b32 v54, v50, 14, v213
	v_cndmask_b32_e64 v51, v54, v51, s[2:3]
	v_cvt_f64_u32_e32 v[54:55], v51
	v_mad_i64_i32 v[50:51], s[2:3], v50, s68, v[66:67]
	v_lshl_add_u64 v[50:51], v[50:51], 0, v[0:1]
	s_nop 0
	v_mov_b32_e32 v58, v222
	v_mov_b32_e32 v59, v223
	v_mul_f64 v[62:63], v[58:59], v[54:55]
	v_rndne_f64_e32 v[62:63], v[62:63]
	v_fma_f64 v[58:59], v[58:59], v[54:55], -v[62:63]
	v_cvt_f32_f64_e32 v58, v[58:59]
	v_sin_f32_e32 v59, v58
	v_cos_f32_e32 v58, v58
	v_mul_f32_e32 v62, v60, v59
	v_fma_f32 v62, v64, v58, -v62
	v_mul_f32_e32 v58, v60, v58
	v_fmac_f32_e32 v58, v64, v59
	v_cvt_pk_bf16_f32 v58, v58, s0
	global_store_short v[50:51], v58, off offset:64
	v_mov_b32_e32 v58, v224
	v_mov_b32_e32 v59, v225
	v_cvt_pk_bf16_f32 v62, v62, s0
	global_store_short v[50:51], v62, off
	v_mul_f64 v[62:63], v[58:59], v[54:55]
	v_rndne_f64_e32 v[62:63], v[62:63]
	v_fma_f64 v[54:55], v[58:59], v[54:55], -v[62:63]
	v_cvt_f32_f64_e32 v54, v[54:55]
	v_sin_f32_e32 v55, v54
	v_cos_f32_e32 v54, v54
	v_mul_f32_e32 v58, v56, v55
	v_fma_f32 v58, v52, v54, -v58
	v_mul_f32_e32 v54, v56, v54
	v_fmac_f32_e32 v54, v52, v55
	v_cvt_pk_bf16_f32 v58, v58, s0
	v_cvt_pk_bf16_f32 v52, v54, s0
	global_store_short v[50:51], v58, off offset:32
	global_store_short v[50:51], v52, off offset:96

; DEV void rope_cs(int pos, int i, float& c, float& s) {
;   double r = (double)pos * ROPE_REV[i];
;   r -= rint(r);
;   float rf = (float)r;
;   s = __builtin_amdgcn_sinf(rf);
;   c = __builtin_amdgcn_cosf(rf);
; }
; template <int EPI, bool AF32>
; DEV void gemm_tile(const void* Ap, int lda, const u16* Bt, int ldb, int K, int m0, int n0, const Epi& ea, char* smem) {
;     ...
;           const int pos = tok_pos(row);
; #pragma unroll
;           for (int n = 0; n < 2; n++) {
;             const int i = n * 16 + fr;
;             float c, s;
;             rope_cs(pos, i, c, s);
;             const float x1 = acc[m][n][j], x2 = acc[m][n + 2][j];
;             C[(size_t)row * 1536 + cb + i] = f2bf(x1 * c - x2 * s);
;             C[(size_t)row * 1536 + cb + 32 + i] = f2bf(x1 * s + x2 * c);
;           }
.LBB0_291:
	s_andn2_saveexec_b64 s[0:1], s[0:1]
	s_cbranch_execz .LBB0_293
	s_movk_i32 s2, 0x7ffd
	v_cmp_gt_i32_e64 s[2:3], s2, v71
	v_and_b32_e32 v50, 0x1fcf, v73
	v_and_or_b32 v51, v73, 15, v213
	v_cndmask_b32_e64 v50, v51, v50, s[2:3]
	v_mad_i64_i32 v[54:55], s[2:3], v73, s68, v[66:67]
	v_cvt_f64_u32_e32 v[50:51], v50
	s_nop 0
	v_mov_b32_e32 v58, v222
	v_mov_b32_e32 v59, v223
	v_lshl_add_u64 v[54:55], v[54:55], 0, v[0:1]
	v_mul_f64 v[62:63], v[58:59], v[50:51]
	v_rndne_f64_e32 v[62:63], v[62:63]
	v_fma_f64 v[58:59], v[58:59], v[50:51], -v[62:63]
	v_cvt_f32_f64_e32 v52, v[58:59]
	v_sin_f32_e32 v56, v52
	v_cos_f32_e32 v52, v52
	v_mul_f32_e32 v58, v61, v56
	v_fma_f32 v58, v65, v52, -v58
	v_cvt_pk_bf16_f32 v58, v58, s0
	global_store_short v[54:55], v58, off
	v_mov_b32_e32 v58, v224
	v_mov_b32_e32 v59, v225
	v_mul_f32_e32 v52, v61, v52
	v_fmac_f32_e32 v52, v65, v56
	v_cvt_pk_bf16_f32 v52, v52, s0
	global_store_short v[54:55], v52, off offset:64
	v_mul_f64 v[60:61], v[58:59], v[50:51]
	v_rndne_f64_e32 v[60:61], v[60:61]
	v_fma_f64 v[50:51], v[58:59], v[50:51], -v[60:61]
	v_cvt_f32_f64_e32 v50, v[50:51]
	v_sin_f32_e32 v51, v50
	v_cos_f32_e32 v50, v50
	v_mul_f32_e32 v52, v57, v51
	v_fma_f32 v52, v53, v50, -v52
	v_mul_f32_e32 v50, v57, v50
	v_fmac_f32_e32 v50, v53, v51
	v_cvt_pk_bf16_f32 v52, v52, s0
	v_cvt_pk_bf16_f32 v50, v50, s0
	global_store_short v[54:55], v52, off offset:32
	global_store_short v[54:55], v50, off offset:96

; DEV void rope_cs(int pos, int i, float& c, float& s) {
;   double r = (double)pos * ROPE_REV[i];
;   r -= rint(r);
;   float rf = (float)r;
;   s = __builtin_amdgcn_sinf(rf);
;   c = __builtin_amdgcn_cosf(rf);
; }
; template <int EPI, bool AF32>
; DEV void gemm_tile(const void* Ap, int lda, const u16* Bt, int ldb, int K, int m0, int n0, const Epi& ea, char* smem) {
;     ...
;           const int pos = tok_pos(row);
; #pragma unroll
;           for (int n = 0; n < 2; n++) {
;             const int i = n * 16 + fr;
;             float c, s;
;             rope_cs(pos, i, c, s);
;             const float x1 = acc[m][n][j], x2 = acc[m][n + 2][j];
;             C[(size_t)row * 1536 + cb + i] = f2bf(x1 * c - x2 * s);
;             C[(size_t)row * 1536 + cb + 32 + i] = f2bf(x1 * s + x2 * c);
;           }
.LBB0_295:
	s_andn2_saveexec_b64 s[0:1], s[0:1]
	s_cbranch_execz .LBB0_297
	v_cmp_gt_i32_e64 s[2:3], s39, v50
	v_and_b32_e32 v51, 0x1fdc, v50
	v_and_or_b32 v52, v50, 28, v213
	v_cndmask_b32_e64 v51, v52, v51, s[2:3]
	v_cvt_f64_u32_e32 v[52:53], v51
	v_mad_i64_i32 v[50:51], s[2:3], v50, s68, v[66:67]
	v_lshl_add_u64 v[50:51], v[50:51], 0, v[0:1]
	s_nop 0
	v_mov_b32_e32 v54, v222
	v_mov_b32_e32 v55, v223
	v_mul_f64 v[56:57], v[54:55], v[52:53]
	v_rndne_f64_e32 v[56:57], v[56:57]
	v_fma_f64 v[54:55], v[54:55], v[52:53], -v[56:57]
	v_cvt_f32_f64_e32 v54, v[54:55]
	v_sin_f32_e32 v55, v54
	v_cos_f32_e32 v54, v54
	v_mul_f32_e32 v56, v42, v55
	v_mul_f32_e32 v42, v42, v54
	v_fma_f32 v56, v46, v54, -v56
	v_fmac_f32_e32 v42, v46, v55
	v_mov_b32_e32 v54, v224
	v_mov_b32_e32 v55, v225
	v_cvt_pk_bf16_f32 v56, v56, s0
	global_store_short v[50:51], v56, off
	v_cvt_pk_bf16_f32 v42, v42, s0
	global_store_short v[50:51], v42, off offset:64
	v_mul_f64 v[56:57], v[54:55], v[52:53]
	v_rndne_f64_e32 v[56:57], v[56:57]
	v_fma_f64 v[52:53], v[54:55], v[52:53], -v[56:57]
	v_cvt_f32_f64_e32 v42, v[52:53]
	v_sin_f32_e32 v46, v42
	v_cos_f32_e32 v42, v42
	v_mul_f32_e32 v52, v38, v46
	v_mul_f32_e32 v38, v38, v42
	v_fma_f32 v52, v34, v42, -v52
	v_fmac_f32_e32 v38, v34, v46
	v_cvt_pk_bf16_f32 v52, v52, s0
	v_cvt_pk_bf16_f32 v34, v38, s0
	global_store_short v[50:51], v52, off offset:32
	global_store_short v[50:51], v34, off offset:96

; DEV void rope_cs(int pos, int i, float& c, float& s) {
;   double r = (double)pos * ROPE_REV[i];
;   r -= rint(r);
;   float rf = (float)r;
;   s = __builtin_amdgcn_sinf(rf);
;   c = __builtin_amdgcn_cosf(rf);
; }
; template <int EPI, bool AF32>
; DEV void gemm_tile(const void* Ap, int lda, const u16* Bt, int ldb, int K, int m0, int n0, const Epi& ea, char* smem) {
;     ...
;           const int pos = tok_pos(row);
; #pragma unroll
;           for (int n = 0; n < 2; n++) {
;             const int i = n * 16 + fr;
;             float c, s;
;             rope_cs(pos, i, c, s);
;             const float x1 = acc[m][n][j], x2 = acc[m][n + 2][j];
;             C[(size_t)row * 1536 + cb + i] = f2bf(x1 * c - x2 * s);
;             C[(size_t)row * 1536 + cb + 32 + i] = f2bf(x1 * s + x2 * c);
;           }
.LBB0_299:
	s_andn2_saveexec_b64 s[0:1], s[0:1]
	s_cbranch_execz .LBB0_301
	v_cmp_gt_i32_e64 s[2:3], s39, v34
	v_and_b32_e32 v38, 0x1fdd, v34
	v_and_or_b32 v42, v34, 29, v213
	v_cndmask_b32_e64 v38, v42, v38, s[2:3]
	v_mad_i64_i32 v[52:53], s[2:3], v34, s68, v[66:67]
	v_cvt_f64_u32_e32 v[50:51], v38
	s_nop 0
	v_mov_b32_e32 v54, v222
	v_mov_b32_e32 v55, v223
	v_lshl_add_u64 v[52:53], v[52:53], 0, v[0:1]
	v_mul_f64 v[56:57], v[54:55], v[50:51]
	v_rndne_f64_e32 v[56:57], v[56:57]
	v_fma_f64 v[54:55], v[54:55], v[50:51], -v[56:57]
	v_cvt_f32_f64_e32 v34, v[54:55]
	v_sin_f32_e32 v38, v34
	v_cos_f32_e32 v34, v34
	v_mul_f32_e32 v42, v43, v38
	v_fma_f32 v42, v47, v34, -v42
	v_cvt_pk_bf16_f32 v42, v42, s0
	global_store_short v[52:53], v42, off
	v_mul_f32_e32 v34, v43, v34
	v_mov_b32_e32 v42, v224
	v_mov_b32_e32 v43, v225
	v_fmac_f32_e32 v34, v47, v38
	v_cvt_pk_bf16_f32 v34, v34, s0
	global_store_short v[52:53], v34, off offset:64
	v_mul_f64 v[46:47], v[42:43], v[50:51]
	v_rndne_f64_e32 v[46:47], v[46:47]
	v_fma_f64 v[42:43], v[42:43], v[50:51], -v[46:47]
	v_cvt_f32_f64_e32 v34, v[42:43]
	v_sin_f32_e32 v38, v34
	v_cos_f32_e32 v34, v34
	v_mul_f32_e32 v42, v39, v38
	v_fma_f32 v42, v35, v34, -v42
	v_mul_f32_e32 v34, v39, v34
	v_fmac_f32_e32 v34, v35, v38
	v_cvt_pk_bf16_f32 v42, v42, s0
	v_cvt_pk_bf16_f32 v34, v34, s0
	global_store_short v[52:53], v42, off offset:32
	global_store_short v[52:53], v34, off offset:96

; DEV void rope_cs(int pos, int i, float& c, float& s) {
;   double r = (double)pos * ROPE_REV[i];
;   r -= rint(r);
;   float rf = (float)r;
;   s = __builtin_amdgcn_sinf(rf);
;   c = __builtin_amdgcn_cosf(rf);
; }
; template <int EPI, bool AF32>
; DEV void gemm_tile(const void* Ap, int lda, const u16* Bt, int ldb, int K, int m0, int n0, const Epi& ea, char* smem) {
;     ...
;           const int pos = tok_pos(row);
; #pragma unroll
;           for (int n = 0; n < 2; n++) {
;             const int i = n * 16 + fr;
;             float c, s;
;             rope_cs(pos, i, c, s);
;             const float x1 = acc[m][n][j], x2 = acc[m][n + 2][j];
;             C[(size_t)row * 1536 + cb + i] = f2bf(x1 * c - x2 * s);
;             C[(size_t)row * 1536 + cb + 32 + i] = f2bf(x1 * s + x2 * c);
;           }
.LBB0_303:
	s_andn2_saveexec_b64 s[0:1], s[0:1]
	s_cbranch_execz .LBB0_305
	v_cmp_gt_i32_e64 s[2:3], s39, v34
	v_and_b32_e32 v35, 0x1fde, v34
	v_and_or_b32 v38, v34, 30, v213
	v_cndmask_b32_e64 v35, v38, v35, s[2:3]
	v_cvt_f64_u32_e32 v[38:39], v35
	v_mad_i64_i32 v[34:35], s[2:3], v34, s68, v[66:67]
	v_lshl_add_u64 v[34:35], v[34:35], 0, v[0:1]
	s_nop 0
	v_mov_b32_e32 v42, v222
	v_mov_b32_e32 v43, v223
	v_mul_f64 v[46:47], v[42:43], v[38:39]
	v_rndne_f64_e32 v[46:47], v[46:47]
	v_fma_f64 v[42:43], v[42:43], v[38:39], -v[46:47]
	v_cvt_f32_f64_e32 v42, v[42:43]
	v_sin_f32_e32 v43, v42
	v_cos_f32_e32 v42, v42
	v_mul_f32_e32 v46, v44, v43
	v_fma_f32 v46, v48, v42, -v46
	v_mul_f32_e32 v42, v44, v42
	v_fmac_f32_e32 v42, v48, v43
	v_cvt_pk_bf16_f32 v42, v42, s0
	global_store_short v[34:35], v42, off offset:64
	v_mov_b32_e32 v42, v224
	v_mov_b32_e32 v43, v225
	v_cvt_pk_bf16_f32 v46, v46, s0
	global_store_short v[34:35], v46, off
	v_mul_f64 v[46:47], v[42:43], v[38:39]
	v_rndne_f64_e32 v[46:47], v[46:47]
	v_fma_f64 v[38:39], v[42:43], v[38:39], -v[46:47]
	v_cvt_f32_f64_e32 v38, v[38:39]
	v_sin_f32_e32 v39, v38
	v_cos_f32_e32 v38, v38
	v_mul_f32_e32 v42, v40, v39
	v_fma_f32 v42, v36, v38, -v42
	v_mul_f32_e32 v38, v40, v38
	v_fmac_f32_e32 v38, v36, v39
	v_cvt_pk_bf16_f32 v42, v42, s0
	v_cvt_pk_bf16_f32 v36, v38, s0
	global_store_short v[34:35], v42, off offset:32
	global_store_short v[34:35], v36, off offset:96

; DEV void rope_cs(int pos, int i, float& c, float& s) {
;   double r = (double)pos * ROPE_REV[i];
;   r -= rint(r);
;   float rf = (float)r;
;   s = __builtin_amdgcn_sinf(rf);
;   c = __builtin_amdgcn_cosf(rf);
; }
; template <int EPI, bool AF32>
; DEV void gemm_tile(const void* Ap, int lda, const u16* Bt, int ldb, int K, int m0, int n0, const Epi& ea, char* smem) {
;     ...
;           const int pos = tok_pos(row);
; #pragma unroll
;           for (int n = 0; n < 2; n++) {
;             const int i = n * 16 + fr;
;             float c, s;
;             rope_cs(pos, i, c, s);
;             const float x1 = acc[m][n][j], x2 = acc[m][n + 2][j];
;             C[(size_t)row * 1536 + cb + i] = f2bf(x1 * c - x2 * s);
;             C[(size_t)row * 1536 + cb + 32 + i] = f2bf(x1 * s + x2 * c);
;           }
.LBB0_307:
	s_andn2_saveexec_b64 s[0:1], s[0:1]
	s_cbranch_execz .LBB0_309
	v_cmp_gt_i32_e64 s[2:3], s39, v50
	v_and_b32_e32 v34, 0x1fdf, v50
	v_and_or_b32 v35, v50, 31, v213
	v_cndmask_b32_e64 v34, v35, v34, s[2:3]
	v_mad_i64_i32 v[38:39], s[2:3], v50, s68, v[66:67]
	v_cvt_f64_u32_e32 v[34:35], v34
	s_nop 0
	v_mov_b32_e32 v42, v222
	v_mov_b32_e32 v43, v223
	v_lshl_add_u64 v[38:39], v[38:39], 0, v[0:1]
	v_mul_f64 v[46:47], v[42:43], v[34:35]
	v_rndne_f64_e32 v[46:47], v[46:47]
	v_fma_f64 v[42:43], v[42:43], v[34:35], -v[46:47]
	v_cvt_f32_f64_e32 v36, v[42:43]
	v_sin_f32_e32 v40, v36
	v_cos_f32_e32 v36, v36
	v_mul_f32_e32 v42, v45, v40
	v_fma_f32 v42, v49, v36, -v42
	v_cvt_pk_bf16_f32 v42, v42, s0
	global_store_short v[38:39], v42, off
	v_mov_b32_e32 v42, v224
	v_mov_b32_e32 v43, v225
	v_mul_f32_e32 v36, v45, v36
	v_fmac_f32_e32 v36, v49, v40
	v_cvt_pk_bf16_f32 v36, v36, s0
	global_store_short v[38:39], v36, off offset:64
	v_mul_f64 v[44:45], v[42:43], v[34:35]
	v_rndne_f64_e32 v[44:45], v[44:45]
	v_fma_f64 v[34:35], v[42:43], v[34:35], -v[44:45]
	v_cvt_f32_f64_e32 v34, v[34:35]
	v_sin_f32_e32 v35, v34
	v_cos_f32_e32 v34, v34
	v_mul_f32_e32 v36, v41, v35
	v_fma_f32 v36, v37, v34, -v36
	v_mul_f32_e32 v34, v41, v34
	v_fmac_f32_e32 v34, v37, v35
	v_cvt_pk_bf16_f32 v36, v36, s0
	v_cvt_pk_bf16_f32 v34, v34, s0
	global_store_short v[38:39], v36, off offset:32
	global_store_short v[38:39], v34, off offset:96

; DEV void rope_cs(int pos, int i, float& c, float& s) {
;   double r = (double)pos * ROPE_REV[i];
;   r -= rint(r);
;   float rf = (float)r;
;   s = __builtin_amdgcn_sinf(rf);
;   c = __builtin_amdgcn_cosf(rf);
; }
; template <int EPI, bool AF32>
; DEV void gemm_tile(const void* Ap, int lda, const u16* Bt, int ldb, int K, int m0, int n0, const Epi& ea, char* smem) {
;     ...
;           const int pos = tok_pos(row);
; #pragma unroll
;           for (int n = 0; n < 2; n++) {
;             const int i = n * 16 + fr;
;             float c, s;
;             rope_cs(pos, i, c, s);
;             const float x1 = acc[m][n][j], x2 = acc[m][n + 2][j];
;             C[(size_t)row * 1536 + cb + i] = f2bf(x1 * c - x2 * s);
;             C[(size_t)row * 1536 + cb + 32 + i] = f2bf(x1 * s + x2 * c);
;           }
.LBB0_311:
	s_andn2_saveexec_b64 s[0:1], s[0:1]
	s_cbranch_execz .LBB0_313
	v_cmp_gt_i32_e64 s[2:3], s39, v34
	v_and_b32_e32 v35, 0x1fec, v34
	s_nop 0
	v_cndmask_b32_e64 v35, v72, v35, s[2:3]
	v_cvt_f64_u32_e32 v[36:37], v35
	v_mad_i64_i32 v[34:35], s[2:3], v34, s68, v[66:67]
	v_lshl_add_u64 v[34:35], v[34:35], 0, v[0:1]
	s_nop 0
	v_mov_b32_e32 v38, v222
	v_mov_b32_e32 v39, v223
	v_mul_f64 v[40:41], v[38:39], v[36:37]
	v_rndne_f64_e32 v[40:41], v[40:41]
	v_fma_f64 v[38:39], v[38:39], v[36:37], -v[40:41]
	v_cvt_f32_f64_e32 v38, v[38:39]
	v_sin_f32_e32 v39, v38
	v_cos_f32_e32 v38, v38
	v_mul_f32_e32 v40, v26, v39
	v_mul_f32_e32 v26, v26, v38
	v_fma_f32 v40, v30, v38, -v40
	v_fmac_f32_e32 v26, v30, v39
	v_mov_b32_e32 v38, v224
	v_mov_b32_e32 v39, v225
	v_cvt_pk_bf16_f32 v40, v40, s0
	global_store_short v[34:35], v40, off
	v_cvt_pk_bf16_f32 v26, v26, s0
	global_store_short v[34:35], v26, off offset:64
	v_mul_f64 v[40:41], v[38:39], v[36:37]
	v_rndne_f64_e32 v[40:41], v[40:41]
	v_fma_f64 v[36:37], v[38:39], v[36:37], -v[40:41]
	v_cvt_f32_f64_e32 v26, v[36:37]
	v_sin_f32_e32 v30, v26
	v_cos_f32_e32 v26, v26
	v_mul_f32_e32 v36, v22, v30
	v_mul_f32_e32 v22, v22, v26
	v_fma_f32 v36, v18, v26, -v36
	v_fmac_f32_e32 v22, v18, v30
	v_cvt_pk_bf16_f32 v36, v36, s0
	v_cvt_pk_bf16_f32 v18, v22, s0
	global_store_short v[34:35], v36, off offset:32
	global_store_short v[34:35], v18, off offset:96

; DEV void rope_cs(int pos, int i, float& c, float& s) {
;   double r = (double)pos * ROPE_REV[i];
;   r -= rint(r);
;   float rf = (float)r;
;   s = __builtin_amdgcn_sinf(rf);
;   c = __builtin_amdgcn_cosf(rf);
; }
; template <int EPI, bool AF32>
; DEV void gemm_tile(const void* Ap, int lda, const u16* Bt, int ldb, int K, int m0, int n0, const Epi& ea, char* smem) {
;     ...
;           const int pos = tok_pos(row);
; #pragma unroll
;           for (int n = 0; n < 2; n++) {
;             const int i = n * 16 + fr;
;             float c, s;
;             rope_cs(pos, i, c, s);
;             const float x1 = acc[m][n][j], x2 = acc[m][n + 2][j];
;             C[(size_t)row * 1536 + cb + i] = f2bf(x1 * c - x2 * s);
;             C[(size_t)row * 1536 + cb + 32 + i] = f2bf(x1 * s + x2 * c);
;           }
.LBB0_315:
	s_andn2_saveexec_b64 s[0:1], s[0:1]
	s_cbranch_execz .LBB0_317
	v_cmp_gt_i32_e64 s[2:3], s39, v18
	v_and_b32_e32 v22, 0x1fed, v18
	v_and_or_b32 v26, v18, 13, v213
	v_cndmask_b32_e64 v22, v26, v22, s[2:3]
	v_mad_i64_i32 v[36:37], s[2:3], v18, s68, v[66:67]
	v_cvt_f64_u32_e32 v[34:35], v22
	s_nop 0
	v_mov_b32_e32 v38, v222
	v_mov_b32_e32 v39, v223
	v_lshl_add_u64 v[36:37], v[36:37], 0, v[0:1]
	v_mul_f64 v[40:41], v[38:39], v[34:35]
	v_rndne_f64_e32 v[40:41], v[40:41]
	v_fma_f64 v[38:39], v[38:39], v[34:35], -v[40:41]
	v_cvt_f32_f64_e32 v18, v[38:39]
	v_sin_f32_e32 v22, v18
	v_cos_f32_e32 v18, v18
	v_mul_f32_e32 v26, v27, v22
	v_fma_f32 v26, v31, v18, -v26
	v_cvt_pk_bf16_f32 v26, v26, s0
	global_store_short v[36:37], v26, off
	v_mul_f32_e32 v18, v27, v18
	v_mov_b32_e32 v26, v224
	v_mov_b32_e32 v27, v225
	v_fmac_f32_e32 v18, v31, v22
	v_cvt_pk_bf16_f32 v18, v18, s0
	global_store_short v[36:37], v18, off offset:64
	v_mul_f64 v[30:31], v[26:27], v[34:35]
	v_rndne_f64_e32 v[30:31], v[30:31]
	v_fma_f64 v[26:27], v[26:27], v[34:35], -v[30:31]
	v_cvt_f32_f64_e32 v18, v[26:27]
	v_sin_f32_e32 v22, v18
	v_cos_f32_e32 v18, v18
	v_mul_f32_e32 v26, v23, v22
	v_fma_f32 v26, v19, v18, -v26
	v_mul_f32_e32 v18, v23, v18
	v_fmac_f32_e32 v18, v19, v22
	v_cvt_pk_bf16_f32 v26, v26, s0
	v_cvt_pk_bf16_f32 v18, v18, s0
	global_store_short v[36:37], v26, off offset:32
	global_store_short v[36:37], v18, off offset:96

; DEV void rope_cs(int pos, int i, float& c, float& s) {
;   double r = (double)pos * ROPE_REV[i];
;   r -= rint(r);
;   float rf = (float)r;
;   s = __builtin_amdgcn_sinf(rf);
;   c = __builtin_amdgcn_cosf(rf);
; }
; template <int EPI, bool AF32>
; DEV void gemm_tile(const void* Ap, int lda, const u16* Bt, int ldb, int K, int m0, int n0, const Epi& ea, char* smem) {
;     ...
;           const int pos = tok_pos(row);
; #pragma unroll
;           for (int n = 0; n < 2; n++) {
;             const int i = n * 16 + fr;
;             float c, s;
;             rope_cs(pos, i, c, s);
;             const float x1 = acc[m][n][j], x2 = acc[m][n + 2][j];
;             C[(size_t)row * 1536 + cb + i] = f2bf(x1 * c - x2 * s);
;             C[(size_t)row * 1536 + cb + 32 + i] = f2bf(x1 * s + x2 * c);
;           }
.LBB0_319:
	s_andn2_saveexec_b64 s[0:1], s[0:1]
	s_cbranch_execz .LBB0_321
	v_cmp_gt_i32_e64 s[2:3], s39, v18
	v_and_b32_e32 v19, 0x1fee, v18
	v_and_or_b32 v22, v18, 14, v213
	v_cndmask_b32_e64 v19, v22, v19, s[2:3]
	v_cvt_f64_u32_e32 v[22:23], v19
	v_mad_i64_i32 v[18:19], s[2:3], v18, s68, v[66:67]
	v_lshl_add_u64 v[18:19], v[18:19], 0, v[0:1]
	s_nop 0
	v_mov_b32_e32 v26, v222
	v_mov_b32_e32 v27, v223
	v_mul_f64 v[30:31], v[26:27], v[22:23]
	v_rndne_f64_e32 v[30:31], v[30:31]
	v_fma_f64 v[26:27], v[26:27], v[22:23], -v[30:31]
	v_cvt_f32_f64_e32 v26, v[26:27]
	v_sin_f32_e32 v27, v26
	v_cos_f32_e32 v26, v26
	v_mul_f32_e32 v30, v28, v27
	v_fma_f32 v30, v32, v26, -v30
	v_mul_f32_e32 v26, v28, v26
	v_fmac_f32_e32 v26, v32, v27
	v_cvt_pk_bf16_f32 v26, v26, s0
	global_store_short v[18:19], v26, off offset:64
	v_mov_b32_e32 v26, v224
	v_mov_b32_e32 v27, v225
	v_cvt_pk_bf16_f32 v30, v30, s0
	global_store_short v[18:19], v30, off
	v_mul_f64 v[30:31], v[26:27], v[22:23]
	v_rndne_f64_e32 v[30:31], v[30:31]
	v_fma_f64 v[22:23], v[26:27], v[22:23], -v[30:31]
	v_cvt_f32_f64_e32 v22, v[22:23]
	v_sin_f32_e32 v23, v22
	v_cos_f32_e32 v22, v22
	v_mul_f32_e32 v26, v24, v23
	v_fma_f32 v26, v20, v22, -v26
	v_mul_f32_e32 v22, v24, v22
	v_fmac_f32_e32 v22, v20, v23
	v_cvt_pk_bf16_f32 v26, v26, s0
	v_cvt_pk_bf16_f32 v20, v22, s0
	global_store_short v[18:19], v26, off offset:32
	global_store_short v[18:19], v20, off offset:96

; DEV void rope_cs(int pos, int i, float& c, float& s) {
;   double r = (double)pos * ROPE_REV[i];
;   r -= rint(r);
;   float rf = (float)r;
;   s = __builtin_amdgcn_sinf(rf);
;   c = __builtin_amdgcn_cosf(rf);
; }
; template <int EPI, bool AF32>
; DEV void gemm_tile(const void* Ap, int lda, const u16* Bt, int ldb, int K, int m0, int n0, const Epi& ea, char* smem) {
;     ...
;           const int pos = tok_pos(row);
; #pragma unroll
;           for (int n = 0; n < 2; n++) {
;             const int i = n * 16 + fr;
;             float c, s;
;             rope_cs(pos, i, c, s);
;             const float x1 = acc[m][n][j], x2 = acc[m][n + 2][j];
;             C[(size_t)row * 1536 + cb + i] = f2bf(x1 * c - x2 * s);
;             C[(size_t)row * 1536 + cb + 32 + i] = f2bf(x1 * s + x2 * c);
;           }
.LBB0_323:
	s_andn2_saveexec_b64 s[0:1], s[0:1]
	s_cbranch_execz .LBB0_325
	v_cmp_gt_i32_e64 s[2:3], s39, v34
	v_and_b32_e32 v18, 0x1fef, v34
	v_and_or_b32 v19, v34, 15, v213
	v_cndmask_b32_e64 v18, v19, v18, s[2:3]
	v_mad_i64_i32 v[22:23], s[2:3], v34, s68, v[66:67]
	v_cvt_f64_u32_e32 v[18:19], v18
	s_nop 0
	v_mov_b32_e32 v26, v222
	v_mov_b32_e32 v27, v223
	v_lshl_add_u64 v[22:23], v[22:23], 0, v[0:1]
	v_mul_f64 v[30:31], v[26:27], v[18:19]
	v_rndne_f64_e32 v[30:31], v[30:31]
	v_fma_f64 v[26:27], v[26:27], v[18:19], -v[30:31]
	v_cvt_f32_f64_e32 v20, v[26:27]
	v_sin_f32_e32 v24, v20
	v_cos_f32_e32 v20, v20
	v_mul_f32_e32 v26, v29, v24
	v_fma_f32 v26, v33, v20, -v26
	v_cvt_pk_bf16_f32 v26, v26, s0
	global_store_short v[22:23], v26, off
	v_mov_b32_e32 v26, v224
	v_mov_b32_e32 v27, v225
	v_mul_f32_e32 v20, v29, v20
	v_fmac_f32_e32 v20, v33, v24
	v_cvt_pk_bf16_f32 v20, v20, s0
	global_store_short v[22:23], v20, off offset:64
	v_mul_f64 v[28:29], v[26:27], v[18:19]
	v_rndne_f64_e32 v[28:29], v[28:29]
	v_fma_f64 v[18:19], v[26:27], v[18:19], -v[28:29]
	v_cvt_f32_f64_e32 v18, v[18:19]
	v_sin_f32_e32 v19, v18
	v_cos_f32_e32 v18, v18
	v_mul_f32_e32 v20, v25, v19
	v_fma_f32 v20, v21, v18, -v20
	v_mul_f32_e32 v18, v25, v18
	v_fmac_f32_e32 v18, v21, v19
	v_cvt_pk_bf16_f32 v20, v20, s0
	v_cvt_pk_bf16_f32 v18, v18, s0
	global_store_short v[22:23], v20, off offset:32
	global_store_short v[22:23], v18, off offset:96

; DEV void rope_cs(int pos, int i, float& c, float& s) {
;   double r = (double)pos * ROPE_REV[i];
;   r -= rint(r);
;   float rf = (float)r;
;   s = __builtin_amdgcn_sinf(rf);
;   c = __builtin_amdgcn_cosf(rf);
; }
; template <int EPI, bool AF32>
; DEV void gemm_tile(const void* Ap, int lda, const u16* Bt, int ldb, int K, int m0, int n0, const Epi& ea, char* smem) {
;     ...
;           const int pos = tok_pos(row);
; #pragma unroll
;           for (int n = 0; n < 2; n++) {
;             const int i = n * 16 + fr;
;             float c, s;
;             rope_cs(pos, i, c, s);
;             const float x1 = acc[m][n][j], x2 = acc[m][n + 2][j];
;             C[(size_t)row * 1536 + cb + i] = f2bf(x1 * c - x2 * s);
;             C[(size_t)row * 1536 + cb + 32 + i] = f2bf(x1 * s + x2 * c);
;           }
.LBB0_327:
	s_andn2_saveexec_b64 s[0:1], s[0:1]
	s_cbranch_execz .LBB0_329
	v_cmp_gt_i32_e64 s[2:3], s39, v18
	v_and_b32_e32 v19, 0x1ffc, v18
	v_and_or_b32 v20, v18, 28, v213
	v_cndmask_b32_e64 v19, v20, v19, s[2:3]
	v_cvt_f64_u32_e32 v[20:21], v19
	v_mad_i64_i32 v[18:19], s[2:3], v18, s68, v[66:67]
	v_lshl_add_u64 v[18:19], v[18:19], 0, v[0:1]
	s_nop 0
	v_mov_b32_e32 v22, v222
	v_mov_b32_e32 v23, v223
	v_mul_f64 v[24:25], v[22:23], v[20:21]
	v_rndne_f64_e32 v[24:25], v[24:25]
	v_fma_f64 v[22:23], v[22:23], v[20:21], -v[24:25]
	v_cvt_f32_f64_e32 v22, v[22:23]
	v_sin_f32_e32 v23, v22
	v_cos_f32_e32 v22, v22
	v_mul_f32_e32 v24, v10, v23
	v_mul_f32_e32 v10, v10, v22
	v_fma_f32 v24, v14, v22, -v24
	v_fmac_f32_e32 v10, v14, v23
	v_mov_b32_e32 v22, v224
	v_mov_b32_e32 v23, v225
	v_cvt_pk_bf16_f32 v24, v24, s0
	global_store_short v[18:19], v24, off
	v_cvt_pk_bf16_f32 v10, v10, s0
	global_store_short v[18:19], v10, off offset:64
	v_mul_f64 v[24:25], v[22:23], v[20:21]
	v_rndne_f64_e32 v[24:25], v[24:25]
	v_fma_f64 v[20:21], v[22:23], v[20:21], -v[24:25]
	v_cvt_f32_f64_e32 v10, v[20:21]
	v_sin_f32_e32 v14, v10
	v_cos_f32_e32 v10, v10
	v_mul_f32_e32 v20, v6, v14
	v_mul_f32_e32 v6, v6, v10
	v_fma_f32 v20, v2, v10, -v20
	v_fmac_f32_e32 v6, v2, v14
	v_cvt_pk_bf16_f32 v20, v20, s0
	v_cvt_pk_bf16_f32 v2, v6, s0
	global_store_short v[18:19], v20, off offset:32
	global_store_short v[18:19], v2, off offset:96

; DEV void rope_cs(int pos, int i, float& c, float& s) {
;   double r = (double)pos * ROPE_REV[i];
;   r -= rint(r);
;   float rf = (float)r;
;   s = __builtin_amdgcn_sinf(rf);
;   c = __builtin_amdgcn_cosf(rf);
; }
; template <int EPI, bool AF32>
; DEV void gemm_tile(const void* Ap, int lda, const u16* Bt, int ldb, int K, int m0, int n0, const Epi& ea, char* smem) {
;     ...
;           const int pos = tok_pos(row);
; #pragma unroll
;           for (int n = 0; n < 2; n++) {
;             const int i = n * 16 + fr;
;             float c, s;
;             rope_cs(pos, i, c, s);
;             const float x1 = acc[m][n][j], x2 = acc[m][n + 2][j];
;             C[(size_t)row * 1536 + cb + i] = f2bf(x1 * c - x2 * s);
;             C[(size_t)row * 1536 + cb + 32 + i] = f2bf(x1 * s + x2 * c);
;           }
.LBB0_331:
	s_andn2_saveexec_b64 s[0:1], s[0:1]
	s_cbranch_execz .LBB0_333
	v_cmp_gt_i32_e64 s[2:3], s39, v2
	v_and_b32_e32 v6, 0x1ffd, v2
	v_and_or_b32 v10, v2, 29, v213
	v_cndmask_b32_e64 v6, v10, v6, s[2:3]
	v_mad_i64_i32 v[20:21], s[2:3], v2, s68, v[66:67]
	v_cvt_f64_u32_e32 v[18:19], v6
	s_nop 0
	v_mov_b32_e32 v22, v222
	v_mov_b32_e32 v23, v223
	v_lshl_add_u64 v[20:21], v[20:21], 0, v[0:1]
	v_mul_f64 v[24:25], v[22:23], v[18:19]
	v_rndne_f64_e32 v[24:25], v[24:25]
	v_fma_f64 v[22:23], v[22:23], v[18:19], -v[24:25]
	v_cvt_f32_f64_e32 v2, v[22:23]
	v_sin_f32_e32 v6, v2
	v_cos_f32_e32 v2, v2
	v_mul_f32_e32 v10, v11, v6
	v_fma_f32 v10, v15, v2, -v10
	v_cvt_pk_bf16_f32 v10, v10, s0
	global_store_short v[20:21], v10, off
	v_mul_f32_e32 v2, v11, v2
	v_mov_b32_e32 v10, v224
	v_mov_b32_e32 v11, v225
	v_fmac_f32_e32 v2, v15, v6
	v_cvt_pk_bf16_f32 v2, v2, s0
	global_store_short v[20:21], v2, off offset:64
	v_mul_f64 v[14:15], v[10:11], v[18:19]
	v_rndne_f64_e32 v[14:15], v[14:15]
	v_fma_f64 v[10:11], v[10:11], v[18:19], -v[14:15]
	v_cvt_f32_f64_e32 v2, v[10:11]
	v_sin_f32_e32 v6, v2
	v_cos_f32_e32 v2, v2
	v_mul_f32_e32 v10, v7, v6
	v_fma_f32 v10, v3, v2, -v10
	v_mul_f32_e32 v2, v7, v2
	v_fmac_f32_e32 v2, v3, v6
	v_cvt_pk_bf16_f32 v10, v10, s0
	v_cvt_pk_bf16_f32 v2, v2, s0
	global_store_short v[20:21], v10, off offset:32
	global_store_short v[20:21], v2, off offset:96

; DEV void rope_cs(int pos, int i, float& c, float& s) {
;   double r = (double)pos * ROPE_REV[i];
;   r -= rint(r);
;   float rf = (float)r;
;   s = __builtin_amdgcn_sinf(rf);
;   c = __builtin_amdgcn_cosf(rf);
; }
; template <int EPI, bool AF32>
; DEV void gemm_tile(const void* Ap, int lda, const u16* Bt, int ldb, int K, int m0, int n0, const Epi& ea, char* smem) {
;     ...
;           const int pos = tok_pos(row);
; #pragma unroll
;           for (int n = 0; n < 2; n++) {
;             const int i = n * 16 + fr;
;             float c, s;
;             rope_cs(pos, i, c, s);
;             const float x1 = acc[m][n][j], x2 = acc[m][n + 2][j];
;             C[(size_t)row * 1536 + cb + i] = f2bf(x1 * c - x2 * s);
;             C[(size_t)row * 1536 + cb + 32 + i] = f2bf(x1 * s + x2 * c);
;           }
.LBB0_335:
	s_andn2_saveexec_b64 s[0:1], s[0:1]
	s_cbranch_execz .LBB0_337
	v_cmp_gt_i32_e64 s[2:3], s39, v2
	v_and_b32_e32 v3, 0x1ffe, v2
	v_and_or_b32 v6, v2, 30, v213
	v_cndmask_b32_e64 v3, v6, v3, s[2:3]
	v_cvt_f64_u32_e32 v[6:7], v3
	v_mad_i64_i32 v[2:3], s[2:3], v2, s68, v[66:67]
	v_lshl_add_u64 v[2:3], v[2:3], 0, v[0:1]
	s_nop 0
	v_mov_b32_e32 v10, v222
	v_mov_b32_e32 v11, v223
	v_mul_f64 v[14:15], v[10:11], v[6:7]
	v_rndne_f64_e32 v[14:15], v[14:15]
	v_fma_f64 v[10:11], v[10:11], v[6:7], -v[14:15]
	v_cvt_f32_f64_e32 v10, v[10:11]
	v_sin_f32_e32 v11, v10
	v_cos_f32_e32 v10, v10
	v_mul_f32_e32 v14, v12, v11
	v_fma_f32 v14, v16, v10, -v14
	v_mul_f32_e32 v10, v12, v10
	v_fmac_f32_e32 v10, v16, v11
	v_cvt_pk_bf16_f32 v10, v10, s0
	global_store_short v[2:3], v10, off offset:64
	v_mov_b32_e32 v10, v224
	v_mov_b32_e32 v11, v225
	v_cvt_pk_bf16_f32 v14, v14, s0
	global_store_short v[2:3], v14, off
	v_mul_f64 v[14:15], v[10:11], v[6:7]
	v_rndne_f64_e32 v[14:15], v[14:15]
	v_fma_f64 v[6:7], v[10:11], v[6:7], -v[14:15]
	v_cvt_f32_f64_e32 v6, v[6:7]
	v_sin_f32_e32 v7, v6
	v_cos_f32_e32 v6, v6
	v_mul_f32_e32 v10, v8, v7
	v_fma_f32 v10, v4, v6, -v10
	v_mul_f32_e32 v6, v8, v6
	v_fmac_f32_e32 v6, v4, v7
	v_cvt_pk_bf16_f32 v10, v10, s0
	v_cvt_pk_bf16_f32 v4, v6, s0
	global_store_short v[2:3], v10, off offset:32
	global_store_short v[2:3], v4, off offset:96

; DEV void rope_cs(int pos, int i, float& c, float& s) {
;   double r = (double)pos * ROPE_REV[i];
;   r -= rint(r);
;   float rf = (float)r;
;   s = __builtin_amdgcn_sinf(rf);
;   c = __builtin_amdgcn_cosf(rf);
; }
; template <int EPI, bool AF32>
; DEV void gemm_tile(const void* Ap, int lda, const u16* Bt, int ldb, int K, int m0, int n0, const Epi& ea, char* smem) {
;     ...
;           const int pos = tok_pos(row);
; #pragma unroll
;           for (int n = 0; n < 2; n++) {
;             const int i = n * 16 + fr;
;             float c, s;
;             rope_cs(pos, i, c, s);
;             const float x1 = acc[m][n][j], x2 = acc[m][n + 2][j];
;             C[(size_t)row * 1536 + cb + i] = f2bf(x1 * c - x2 * s);
;             C[(size_t)row * 1536 + cb + 32 + i] = f2bf(x1 * s + x2 * c);
;           }
.LBB0_339:
	s_andn2_saveexec_b64 s[0:1], s[0:1]
	s_cbranch_execz .LBB0_276
	v_mad_i64_i32 v[6:7], s[2:3], v18, s68, v[66:67]
	v_cmp_gt_i32_e32 vcc, s39, v18
	s_nop 0
	v_mov_b32_e32 v10, v222
	v_mov_b32_e32 v11, v223
	v_and_b32_e32 v2, 0x1fff, v18
	v_and_or_b32 v3, v18, 31, v213
	v_cndmask_b32_e32 v2, v3, v2, vcc
	v_cvt_f64_u32_e32 v[2:3], v2
	v_lshl_add_u64 v[6:7], v[6:7], 0, v[0:1]
	v_mul_f64 v[14:15], v[10:11], v[2:3]
	v_rndne_f64_e32 v[14:15], v[14:15]
	v_fma_f64 v[10:11], v[10:11], v[2:3], -v[14:15]
	v_cvt_f32_f64_e32 v4, v[10:11]
	v_sin_f32_e32 v8, v4
	v_cos_f32_e32 v4, v4
	v_mul_f32_e32 v10, v13, v8
	v_fma_f32 v10, v17, v4, -v10
	v_cvt_pk_bf16_f32 v10, v10, s0
	global_store_short v[6:7], v10, off
	v_mov_b32_e32 v10, v224
	v_mov_b32_e32 v11, v225
	v_mul_f32_e32 v0, v13, v4
	v_fmac_f32_e32 v0, v17, v8
	v_cvt_pk_bf16_f32 v0, v0, s0
	global_store_short v[6:7], v0, off offset:64
	v_mul_f64 v[12:13], v[10:11], v[2:3]
	v_rndne_f64_e32 v[12:13], v[12:13]
	v_fma_f64 v[2:3], v[10:11], v[2:3], -v[12:13]
	v_cvt_f32_f64_e32 v0, v[2:3]
	v_sin_f32_e32 v2, v0
	v_cos_f32_e32 v0, v0
	v_mul_f32_e32 v3, v9, v2
	v_fma_f32 v3, v5, v0, -v3
	v_mul_f32_e32 v0, v9, v0
	v_fmac_f32_e32 v0, v5, v2
	v_cvt_pk_bf16_f32 v3, v3, s0
	v_cvt_pk_bf16_f32 v0, v0, s0
	global_store_short v[6:7], v3, off offset:32
	global_store_short v[6:7], v0, off offset:96
	s_branch .LBB0_276
